# GEMM epilogues (SwiGLU and plain): per-row store addresses chained by one 64-bit add per row instead of mad_u64/mul_lo/add3 recomputation
# speedup vs baseline: 1.0036x; 1.0036x over previous
; #define PG8_STAGE(bufoff, gbase, voff) do { _Pragma("unroll") for (int _i = 0; _i < 2; ++_i) \
;         __builtin_amdgcn_global_load_lds((const unsigned*)((const char*)(gbase) + (voff)[_i]), (LAS unsigned*)(lds + (bufoff) + ldsw + _i * 8192), 16, 0, 0); } while (0)
; #define PG8_LDA(dst, b, h) do { _Pragma("unroll") for (int m = 0; m < 4; ++m) _Pragma("unroll") for (int k = 0; k < 2; ++k) dst[m][k] = *(const LAS bf16x8*)(lds + PG8_SA(b, h) + aoff + m * 2048 + k * 1024); } while (0)
; #define PG8_WAIT_V(n) asm volatile("s_waitcnt vmcnt(" #n ")" ::: "memory")
; #define PG8_WAIT_L(n) asm volatile("s_waitcnt lgkmcnt(" #n ")" ::: "memory")
; template <class Epi>
; DI void gemm_phase(LAS unsigned char* lds, const Gemm g, const StaticOrder& S, const Epi& E, const int tid) {
;     ...
;         for (int t = 0; t < nt; t += 2) {
;             const bool last = (t == nt - 2);
;             const char* a1 = cA + (size_t)(t + 1) * kstep;
;             const char* a2 = last ? nA : cA + (size_t)(t + 2) * kstep; const char* b2 = last ? nB : cB + (size_t)(t + 2) * kstep;
;             const char* a3 = a2 + kstep; const char* b3 = b2 + kstep;
;             PG8_LDB(B0, 0, 0); PG8_SCHED; PG8_LDA(At, 0, 0); PG8_STAGE(PG8_SA(1, 1), a1 + hstep, voffA);
;             PG8_WAIT_L(8); PG8_BAR; PG8_WAIT_L(0); PG8_MMA(0, 0, At, B0); PG8_BAR; PG8_SCHED;
;             PG8_LDB(B1, 0, 1); PG8_STAGE(PG8_SB(0, 0), b2, voffB);
;             PG8_BAR; PG8_WAIT_L(0); PG8_MMA(0, 1, At, B1); PG8_BAR;
;             PG8_LDA(At, 0, 1); PG8_STAGE(PG8_SA(0, 0), a2, voffA);
;             PG8_BAR; PG8_WAIT_L(0); PG8_MMA(1, 0, At, B0); PG8_BAR; PG8_SCHED;
;             PG8_STAGE(PG8_SB(0, 1), b2 + hstep, voffB);
;             PG8_WAIT_V(6); PG8_BAR; PG8_MMA(1, 1, At, B1); PG8_BAR;
;             PG8_LDB(B0, 1, 0); PG8_SCHED; PG8_LDA(At, 1, 0); PG8_STAGE(PG8_SA(0, 1), a2 + hstep, voffA);
;             PG8_WAIT_L(8); PG8_BAR; PG8_WAIT_L(0); PG8_MMA(0, 0, At, B0); PG8_BAR; PG8_SCHED;
;             PG8_LDB(B1, 1, 1); PG8_STAGE(PG8_SB(1, 0), b3, voffB);
;             PG8_BAR; PG8_WAIT_L(0); PG8_MMA(0, 1, At, B1); PG8_BAR;
;             PG8_LDA(At, 1, 1); PG8_STAGE(PG8_SA(1, 0), a3, voffA);
;             PG8_BAR; PG8_WAIT_L(0); PG8_MMA(1, 0, At, B0); PG8_BAR; PG8_SCHED;
;             PG8_STAGE(PG8_SB(1, 1), b3 + hstep, voffB);
;             PG8_WAIT_V(6); PG8_BAR; PG8_MMA(1, 1, At, B1); PG8_BAR;
.LBB0_743:
	ds_read_b128 v[138:141], v212
	ds_read_b128 v[150:153], v212 offset:1024
	ds_read_b128 v[154:157], v212 offset:2048
	ds_read_b128 v[158:161], v212 offset:3072
	s_add_i32 s83, s18, 2
	s_add_u32 s22, s20, 0x80
	s_addc_u32 s19, s21, 0
	s_cmp_eq_u32 s60, s18
	s_cselect_b32 s18, s8, s22
	s_cselect_b32 s19, s9, s19
	s_cselect_b32 s23, s17, s82
	s_cselect_b32 s22, s16, s81
	s_add_i32 m0, s49, 0xc000
	ds_read_b128 v[162:165], v148
	ds_read_b128 v[166:169], v148 offset:1024
	ds_read_b128 v[170:173], v148 offset:2048
	ds_read_b128 v[174:177], v148 offset:3072
	ds_read_b128 v[178:181], v148 offset:4096
	ds_read_b128 v[182:185], v148 offset:5120
	ds_read_b128 v[186:189], v148 offset:6144
	ds_read_b128 v[190:193], v148 offset:7168
	global_load_lds_dwordx4 v134, s[20:21]
	s_add_i32 m0, s49, 0xe000
	s_nop 0
	global_load_lds_dwordx4 v136, s[20:21]
	s_waitcnt lgkmcnt(8)
	s_barrier
	s_waitcnt lgkmcnt(0)
	s_setprio 1
	s_waitcnt lgkmcnt(0)
	v_mfma_f32_16x16x32_bf16 v[24:27], v[138:141], v[162:165], v[24:27]
	v_mfma_f32_16x16x32_bf16 v[28:31], v[154:157], v[162:165], v[28:31]
	v_mfma_f32_16x16x32_bf16 v[16:19], v[138:141], v[170:173], v[16:19]
	v_mfma_f32_16x16x32_bf16 v[20:23], v[154:157], v[170:173], v[20:23]
	v_mfma_f32_16x16x32_bf16 v[8:11], v[138:141], v[178:181], v[8:11]
	v_mfma_f32_16x16x32_bf16 v[12:15], v[154:157], v[178:181], v[12:15]
	v_mfma_f32_16x16x32_bf16 v[0:3], v[138:141], v[186:189], v[0:3]
	v_mfma_f32_16x16x32_bf16 v[4:7], v[154:157], v[186:189], v[4:7]
	v_mfma_f32_16x16x32_bf16 v[24:27], v[150:153], v[166:169], v[24:27]
	v_mfma_f32_16x16x32_bf16 v[28:31], v[158:161], v[166:169], v[28:31]
	v_mfma_f32_16x16x32_bf16 v[16:19], v[150:153], v[174:177], v[16:19]
	v_mfma_f32_16x16x32_bf16 v[20:23], v[158:161], v[174:177], v[20:23]
	v_mfma_f32_16x16x32_bf16 v[8:11], v[150:153], v[182:185], v[8:11]
	v_mfma_f32_16x16x32_bf16 v[12:15], v[158:161], v[182:185], v[12:15]
	v_mfma_f32_16x16x32_bf16 v[0:3], v[150:153], v[190:193], v[0:3]
	v_mfma_f32_16x16x32_bf16 v[4:7], v[158:161], v[190:193], v[4:7]
	s_setprio 0
	s_barrier
	s_add_i32 s89, 0, 0x14000
	s_add_i32 vcc_lo, s26, s4
	s_mov_b32 m0, vcc_lo
	ds_read_b128 v[194:197], v213
	ds_read_b128 v[200:203], v213 offset:1024
	ds_read_b128 v[204:207], v213 offset:2048
	ds_read_b128 v[208:211], v213 offset:3072
	global_load_lds_dwordx4 v198, s[22:23]
	s_add_i32 m0, vcc_lo, 0x2000
	s_nop 0
	global_load_lds_dwordx4 v128, s[22:23]
	s_barrier
	s_waitcnt lgkmcnt(0)
	s_setprio 1
	s_waitcnt lgkmcnt(0)
	v_mfma_f32_16x16x32_bf16 v[88:91], v[194:197], v[162:165], v[88:91]
	v_mfma_f32_16x16x32_bf16 v[96:99], v[204:207], v[162:165], v[96:99]
	v_mfma_f32_16x16x32_bf16 v[80:83], v[194:197], v[170:173], v[80:83]
	v_mfma_f32_16x16x32_bf16 v[84:87], v[204:207], v[170:173], v[84:87]
	v_mfma_f32_16x16x32_bf16 v[72:75], v[194:197], v[178:181], v[72:75]
	v_mfma_f32_16x16x32_bf16 v[76:79], v[204:207], v[178:181], v[76:79]
	v_mfma_f32_16x16x32_bf16 v[56:59], v[194:197], v[186:189], v[56:59]
	v_mfma_f32_16x16x32_bf16 v[64:67], v[204:207], v[186:189], v[64:67]
	v_mfma_f32_16x16x32_bf16 v[88:91], v[200:203], v[166:169], v[88:91]
	v_mfma_f32_16x16x32_bf16 v[96:99], v[208:211], v[166:169], v[96:99]
	v_mfma_f32_16x16x32_bf16 v[80:83], v[200:203], v[174:177], v[80:83]
	v_mfma_f32_16x16x32_bf16 v[84:87], v[208:211], v[174:177], v[84:87]
	v_mfma_f32_16x16x32_bf16 v[72:75], v[200:203], v[182:185], v[72:75]
	v_mfma_f32_16x16x32_bf16 v[76:79], v[208:211], v[182:185], v[76:79]
	v_mfma_f32_16x16x32_bf16 v[56:59], v[200:203], v[190:193], v[56:59]
	v_mfma_f32_16x16x32_bf16 v[64:67], v[208:211], v[190:193], v[64:67]
	s_setprio 0
	s_mov_b32 m0, s49
	s_barrier
	ds_read_b128 v[162:165], v148 offset:16384
	ds_read_b128 v[166:169], v148 offset:17408
	ds_read_b128 v[170:173], v148 offset:18432
	ds_read_b128 v[174:177], v148 offset:19456
	ds_read_b128 v[178:181], v148 offset:20480
	ds_read_b128 v[182:185], v148 offset:21504
	ds_read_b128 v[186:189], v148 offset:22528
	ds_read_b128 v[190:193], v148 offset:23552
	global_load_lds_dwordx4 v132, s[18:19]
	s_mov_b32 m0, s52
	s_nop 0
	global_load_lds_dwordx4 v130, s[18:19]
	s_barrier
	s_waitcnt lgkmcnt(0)
	s_setprio 1
	s_waitcnt lgkmcnt(0)
	v_mfma_f32_16x16x32_bf16 v[60:63], v[138:141], v[162:165], v[60:63]
	v_mfma_f32_16x16x32_bf16 v[68:71], v[154:157], v[162:165], v[68:71]
	v_mfma_f32_16x16x32_bf16 v[48:51], v[138:141], v[170:173], v[48:51]
	v_mfma_f32_16x16x32_bf16 v[52:55], v[154:157], v[170:173], v[52:55]
	v_mfma_f32_16x16x32_bf16 v[40:43], v[138:141], v[178:181], v[40:43]
	v_mfma_f32_16x16x32_bf16 v[44:47], v[154:157], v[178:181], v[44:47]
	v_mfma_f32_16x16x32_bf16 v[32:35], v[138:141], v[186:189], v[32:35]
	v_mfma_f32_16x16x32_bf16 v[36:39], v[154:157], v[186:189], v[36:39]
	v_mfma_f32_16x16x32_bf16 v[60:63], v[150:153], v[166:169], v[60:63]
	v_mfma_f32_16x16x32_bf16 v[68:71], v[158:161], v[166:169], v[68:71]
	v_mfma_f32_16x16x32_bf16 v[48:51], v[150:153], v[174:177], v[48:51]
	v_mfma_f32_16x16x32_bf16 v[52:55], v[158:161], v[174:177], v[52:55]
	v_mfma_f32_16x16x32_bf16 v[40:43], v[150:153], v[182:185], v[40:43]
	v_mfma_f32_16x16x32_bf16 v[44:47], v[158:161], v[182:185], v[44:47]
	v_mfma_f32_16x16x32_bf16 v[32:35], v[150:153], v[190:193], v[32:35]
	v_mfma_f32_16x16x32_bf16 v[36:39], v[158:161], v[190:193], v[36:39]
	s_setprio 0
	s_barrier
	s_add_u32 s22, s22, s84
	s_addc_u32 s23, s23, 0
	s_add_i32 s89, s89, s4
	s_mov_b32 m0, s89
	s_nop 0
	global_load_lds_dwordx4 v198, s[22:23]
	s_add_i32 m0, s89, 0x2000
	s_nop 0
	global_load_lds_dwordx4 v128, s[22:23]
	s_waitcnt vmcnt(6)
	s_barrier
; #define PG8_STAGE(bufoff, gbase, voff) do { _Pragma("unroll") for (int _i = 0; _i < 2; ++_i) \
;         __builtin_amdgcn_global_load_lds((const unsigned*)((const char*)(gbase) + (voff)[_i]), (LAS unsigned*)(lds + (bufoff) + ldsw + _i * 8192), 16, 0, 0); } while (0)
; #define PG8_LDA(dst, b, h) do { _Pragma("unroll") for (int m = 0; m < 4; ++m) _Pragma("unroll") for (int k = 0; k < 2; ++k) dst[m][k] = *(const LAS bf16x8*)(lds + PG8_SA(b, h) + aoff + m * 2048 + k * 1024); } while (0)
; #define PG8_WAIT_V(n) asm volatile("s_waitcnt vmcnt(" #n ")" ::: "memory")
; #define PG8_WAIT_L(n) asm volatile("s_waitcnt lgkmcnt(" #n ")" ::: "memory")
; template <class Epi>
; DI void gemm_phase(LAS unsigned char* lds, const Gemm g, const StaticOrder& S, const Epi& E, const int tid) {
;     ...
;         for (int t = 0; t < nt; t += 2) {
;             const bool last = (t == nt - 2);
;             const char* a1 = cA + (size_t)(t + 1) * kstep;
;             const char* a2 = last ? nA : cA + (size_t)(t + 2) * kstep; const char* b2 = last ? nB : cB + (size_t)(t + 2) * kstep;
;             const char* a3 = a2 + kstep; const char* b3 = b2 + kstep;
;             PG8_LDB(B0, 0, 0); PG8_SCHED; PG8_LDA(At, 0, 0); PG8_STAGE(PG8_SA(1, 1), a1 + hstep, voffA);
;             PG8_WAIT_L(8); PG8_BAR; PG8_WAIT_L(0); PG8_MMA(0, 0, At, B0); PG8_BAR; PG8_SCHED;
;             PG8_LDB(B1, 0, 1); PG8_STAGE(PG8_SB(0, 0), b2, voffB);
;             PG8_BAR; PG8_WAIT_L(0); PG8_MMA(0, 1, At, B1); PG8_BAR;
;             PG8_LDA(At, 0, 1); PG8_STAGE(PG8_SA(0, 0), a2, voffA);
;             PG8_BAR; PG8_WAIT_L(0); PG8_MMA(1, 0, At, B0); PG8_BAR; PG8_SCHED;
;             PG8_STAGE(PG8_SB(0, 1), b2 + hstep, voffB);
;             PG8_WAIT_V(6); PG8_BAR; PG8_MMA(1, 1, At, B1); PG8_BAR;
;             PG8_LDB(B0, 1, 0); PG8_SCHED; PG8_LDA(At, 1, 0); PG8_STAGE(PG8_SA(0, 1), a2 + hstep, voffA);
;             PG8_WAIT_L(8); PG8_BAR; PG8_WAIT_L(0); PG8_MMA(0, 0, At, B0); PG8_BAR; PG8_SCHED;
;             PG8_LDB(B1, 1, 1); PG8_STAGE(PG8_SB(1, 0), b3, voffB);
;             PG8_BAR; PG8_WAIT_L(0); PG8_MMA(0, 1, At, B1); PG8_BAR;
;             PG8_LDA(At, 1, 1); PG8_STAGE(PG8_SA(1, 0), a3, voffA);
;             PG8_BAR; PG8_WAIT_L(0); PG8_MMA(1, 0, At, B0); PG8_BAR; PG8_SCHED;
;             PG8_STAGE(PG8_SB(1, 1), b3 + hstep, voffB);
;             PG8_WAIT_V(6); PG8_BAR; PG8_MMA(1, 1, At, B1); PG8_BAR;
	s_setprio 1
	v_mfma_f32_16x16x32_bf16 v[120:123], v[194:197], v[162:165], v[120:123]
	v_mfma_f32_16x16x32_bf16 v[124:127], v[204:207], v[162:165], v[124:127]
	v_mfma_f32_16x16x32_bf16 v[112:115], v[194:197], v[170:173], v[112:115]
	v_mfma_f32_16x16x32_bf16 v[116:119], v[204:207], v[170:173], v[116:119]
	v_mfma_f32_16x16x32_bf16 v[104:107], v[194:197], v[178:181], v[104:107]
	v_mfma_f32_16x16x32_bf16 v[108:111], v[204:207], v[178:181], v[108:111]
	v_mfma_f32_16x16x32_bf16 v[92:95], v[194:197], v[186:189], v[92:95]
	v_mfma_f32_16x16x32_bf16 v[100:103], v[204:207], v[186:189], v[100:103]
	v_mfma_f32_16x16x32_bf16 v[120:123], v[200:203], v[166:169], v[120:123]
	v_mfma_f32_16x16x32_bf16 v[124:127], v[208:211], v[166:169], v[124:127]
	v_mfma_f32_16x16x32_bf16 v[112:115], v[200:203], v[174:177], v[112:115]
	v_mfma_f32_16x16x32_bf16 v[116:119], v[208:211], v[174:177], v[116:119]
	v_mfma_f32_16x16x32_bf16 v[104:107], v[200:203], v[182:185], v[104:107]
	v_mfma_f32_16x16x32_bf16 v[108:111], v[208:211], v[182:185], v[108:111]
	v_mfma_f32_16x16x32_bf16 v[92:95], v[200:203], v[190:193], v[92:95]
	v_mfma_f32_16x16x32_bf16 v[100:103], v[208:211], v[190:193], v[100:103]
	s_setprio 0
	s_add_i32 s22, 0, 0x18000
	s_barrier
	ds_read_b128 v[138:141], v214
	ds_read_b128 v[150:153], v214 offset:1024
	ds_read_b128 v[154:157], v214 offset:2048
	ds_read_b128 v[158:161], v214 offset:3072
	s_add_u32 s18, s18, s84
	s_addc_u32 s19, s19, 0
	s_mov_b32 m0, s53
	ds_read_b128 v[162:165], v148 offset:32768
	ds_read_b128 v[166:169], v148 offset:33792
	ds_read_b128 v[170:173], v148 offset:34816
	ds_read_b128 v[174:177], v148 offset:35840
	ds_read_b128 v[178:181], v148 offset:36864
	ds_read_b128 v[182:185], v148 offset:37888
	ds_read_b128 v[186:189], v148 offset:38912
	ds_read_b128 v[190:193], v148 offset:39936
	global_load_lds_dwordx4 v132, s[18:19]
	s_mov_b32 m0, s54
	s_nop 0
	global_load_lds_dwordx4 v130, s[18:19]
	s_waitcnt lgkmcnt(8)
	s_barrier
	s_waitcnt lgkmcnt(0)
	s_setprio 1
	s_waitcnt lgkmcnt(0)
	v_mfma_f32_16x16x32_bf16 v[24:27], v[138:141], v[162:165], v[24:27]
	v_mfma_f32_16x16x32_bf16 v[28:31], v[154:157], v[162:165], v[28:31]
	v_mfma_f32_16x16x32_bf16 v[16:19], v[138:141], v[170:173], v[16:19]
	v_mfma_f32_16x16x32_bf16 v[20:23], v[154:157], v[170:173], v[20:23]
	v_mfma_f32_16x16x32_bf16 v[8:11], v[138:141], v[178:181], v[8:11]
	v_mfma_f32_16x16x32_bf16 v[12:15], v[154:157], v[178:181], v[12:15]
	v_mfma_f32_16x16x32_bf16 v[0:3], v[138:141], v[186:189], v[0:3]
	v_mfma_f32_16x16x32_bf16 v[4:7], v[154:157], v[186:189], v[4:7]
	v_mfma_f32_16x16x32_bf16 v[24:27], v[150:153], v[166:169], v[24:27]
	v_mfma_f32_16x16x32_bf16 v[28:31], v[158:161], v[166:169], v[28:31]
	v_mfma_f32_16x16x32_bf16 v[16:19], v[150:153], v[174:177], v[16:19]
	v_mfma_f32_16x16x32_bf16 v[20:23], v[158:161], v[174:177], v[20:23]
	v_mfma_f32_16x16x32_bf16 v[8:11], v[150:153], v[182:185], v[8:11]
	v_mfma_f32_16x16x32_bf16 v[12:15], v[158:161], v[182:185], v[12:15]
	v_mfma_f32_16x16x32_bf16 v[0:3], v[150:153], v[190:193], v[0:3]
	v_mfma_f32_16x16x32_bf16 v[4:7], v[158:161], v[190:193], v[4:7]
	s_setprio 0
	s_barrier
	s_add_i32 s18, 0, 0x1c000
	s_add_i32 s19, s22, s4
	s_mov_b32 m0, s19
	ds_read_b128 v[194:197], v215
	ds_read_b128 v[200:203], v215 offset:1024
	ds_read_b128 v[204:207], v215 offset:2048
	ds_read_b128 v[208:211], v215 offset:3072
	s_add_i32 vcc_hi, s60, 2
	s_cmp_eq_u32 vcc_hi, s83
	s_cselect_b32 s100, s16, s81
	s_cselect_b32 s101, s17, s82
	s_add_u32 s100, s100, 0x80
	s_addc_u32 s101, s101, 0
	global_load_lds_dwordx4 v198, s[100:101]
	s_add_i32 m0, s19, 0x2000
	s_nop 0
	global_load_lds_dwordx4 v128, s[100:101]
	s_barrier
	s_waitcnt lgkmcnt(0)
	s_setprio 1
	s_waitcnt lgkmcnt(0)
	v_mfma_f32_16x16x32_bf16 v[88:91], v[194:197], v[162:165], v[88:91]
	v_mfma_f32_16x16x32_bf16 v[96:99], v[204:207], v[162:165], v[96:99]
	v_mfma_f32_16x16x32_bf16 v[80:83], v[194:197], v[170:173], v[80:83]
	v_mfma_f32_16x16x32_bf16 v[84:87], v[204:207], v[170:173], v[84:87]
	v_mfma_f32_16x16x32_bf16 v[72:75], v[194:197], v[178:181], v[72:75]
	v_mfma_f32_16x16x32_bf16 v[76:79], v[204:207], v[178:181], v[76:79]
	v_mfma_f32_16x16x32_bf16 v[56:59], v[194:197], v[186:189], v[56:59]
	v_mfma_f32_16x16x32_bf16 v[64:67], v[204:207], v[186:189], v[64:67]
	v_mfma_f32_16x16x32_bf16 v[88:91], v[200:203], v[166:169], v[88:91]
	v_mfma_f32_16x16x32_bf16 v[96:99], v[208:211], v[166:169], v[96:99]
	v_mfma_f32_16x16x32_bf16 v[80:83], v[200:203], v[174:177], v[80:83]
	v_mfma_f32_16x16x32_bf16 v[84:87], v[208:211], v[174:177], v[84:87]
	v_mfma_f32_16x16x32_bf16 v[72:75], v[200:203], v[182:185], v[72:75]
	v_mfma_f32_16x16x32_bf16 v[76:79], v[208:211], v[182:185], v[76:79]
	v_mfma_f32_16x16x32_bf16 v[56:59], v[200:203], v[190:193], v[56:59]
	v_mfma_f32_16x16x32_bf16 v[64:67], v[208:211], v[190:193], v[64:67]
	s_setprio 0
	s_mov_b32 m0, s55
	s_barrier
	ds_read_b128 v[162:165], v148 offset:49152
	ds_read_b128 v[166:169], v148 offset:50176
	ds_read_b128 v[170:173], v148 offset:51200
	ds_read_b128 v[174:177], v148 offset:52224
	ds_read_b128 v[178:181], v148 offset:53248
	ds_read_b128 v[182:185], v148 offset:54272
	ds_read_b128 v[186:189], v148 offset:55296
	ds_read_b128 v[190:193], v148 offset:56320
	s_add_u32 s100, s20, 0x80
	s_addc_u32 s101, s21, 0
	s_add_i32 vcc_hi, s60, 2
	s_cmp_eq_u32 vcc_hi, s83
	s_cselect_b32 s100, s8, s100
	s_cselect_b32 s101, s9, s101
	s_add_u32 s100, s100, 0x80
	s_addc_u32 s101, s101, 0
	global_load_lds_dwordx4 v132, s[100:101]
	s_mov_b32 m0, s56
	s_nop 0
	global_load_lds_dwordx4 v130, s[100:101]
	s_barrier
; DI unsigned pk2(float lo, float hi) { f32x2 v = {lo, hi}; bf16v2 b = __builtin_convertvector(v, bf16v2); return __builtin_bit_cast(unsigned, b); }
; DI float silu_f(float x) { return x * __builtin_amdgcn_rcpf(1.f + __expf(-x)); }
; #define PG8_STAGE(bufoff, gbase, voff) do { _Pragma("unroll") for (int _i = 0; _i < 2; ++_i) \
;         __builtin_amdgcn_global_load_lds((const unsigned*)((const char*)(gbase) + (voff)[_i]), (LAS unsigned*)(lds + (bufoff) + ldsw + _i * 8192), 16, 0, 0); } while (0)
; #define PG8_WAIT_V(n) asm volatile("s_waitcnt vmcnt(" #n ")" ::: "memory")
; #define PG8_WAIT_L(n) asm volatile("s_waitcnt lgkmcnt(" #n ")" ::: "memory")
; #define PG8_BAR __builtin_amdgcn_s_barrier()
;     DI void operator()(const f32x4 (&acc)[2][2][4][2], const Unit& u, int wr, int wc, int fr, int fq) const {
;         const int row0 = u.pm * BM + wr * 64 + fr, col0 = u.pn * HALF + wc * 32 + 8 * fq;
; #pragma unroll
;         for (int ai = 0; ai < 2; ++ai)
; #pragma unroll
;             for (int m = 0; m < 4; ++m) { bf16_t* rowp = O + (size_t)(row0 + ai * HALF + m * 16) * ldc + col0;
;                 float r[8];
; #pragma unroll
;                 for (int n = 0; n < 2; ++n)
; #pragma unroll
;                     for (int e = 0; e < 4; ++e) { const float g = acc[ai][0][m][n][e], up = acc[ai][1][m][n][e]; r[n * 4 + e] = silu_f(g) * up; }
;                 u32x4 o; o.x = pk2(r[0], r[1]); o.y = pk2(r[2], r[3]); o.z = pk2(r[4], r[5]); o.w = pk2(r[6], r[7]);
;                 *(u32x4*)rowp = o; }
; template <class Epi>
; DI void gemm_phase(LAS unsigned char* lds, const Gemm g, const StaticOrder& S, const Epi& E, const int tid) {
;     ...
;             PG8_WAIT_V(6); PG8_BAR; PG8_MMA(1, 1, At, B1); PG8_BAR;
;             PG8_LDB(B0, 1, 0); PG8_SCHED; PG8_LDA(At, 1, 0); PG8_STAGE(PG8_SA(0, 1), a2 + hstep, voffA);
;             PG8_WAIT_L(8); PG8_BAR; PG8_WAIT_L(0); PG8_MMA(0, 0, At, B0); PG8_BAR; PG8_SCHED;
;             PG8_LDB(B1, 1, 1); PG8_STAGE(PG8_SB(1, 0), b3, voffB);
;             PG8_BAR; PG8_WAIT_L(0); PG8_MMA(0, 1, At, B1); PG8_BAR;
;             PG8_LDA(At, 1, 1); PG8_STAGE(PG8_SA(1, 0), a3, voffA);
;             PG8_BAR; PG8_WAIT_L(0); PG8_MMA(1, 0, At, B0); PG8_BAR; PG8_SCHED;
;             PG8_STAGE(PG8_SB(1, 1), b3 + hstep, voffB);
;             PG8_WAIT_V(6); PG8_BAR; PG8_MMA(1, 1, At, B1); PG8_BAR;
;         }
;         E(acc, cur, wr, wc, fr, fq);
	s_waitcnt lgkmcnt(0)
	s_setprio 1
	s_waitcnt lgkmcnt(0)
	v_mfma_f32_16x16x32_bf16 v[60:63], v[138:141], v[162:165], v[60:63]
	v_mfma_f32_16x16x32_bf16 v[68:71], v[154:157], v[162:165], v[68:71]
	v_mfma_f32_16x16x32_bf16 v[48:51], v[138:141], v[170:173], v[48:51]
	v_mfma_f32_16x16x32_bf16 v[52:55], v[154:157], v[170:173], v[52:55]
	v_mfma_f32_16x16x32_bf16 v[40:43], v[138:141], v[178:181], v[40:43]
	v_mfma_f32_16x16x32_bf16 v[44:47], v[154:157], v[178:181], v[44:47]
	v_mfma_f32_16x16x32_bf16 v[32:35], v[138:141], v[186:189], v[32:35]
	v_mfma_f32_16x16x32_bf16 v[36:39], v[154:157], v[186:189], v[36:39]
	v_mfma_f32_16x16x32_bf16 v[60:63], v[150:153], v[166:169], v[60:63]
	v_mfma_f32_16x16x32_bf16 v[68:71], v[158:161], v[166:169], v[68:71]
	v_mfma_f32_16x16x32_bf16 v[48:51], v[150:153], v[174:177], v[48:51]
	v_mfma_f32_16x16x32_bf16 v[52:55], v[158:161], v[174:177], v[52:55]
	v_mfma_f32_16x16x32_bf16 v[40:43], v[150:153], v[182:185], v[40:43]
	v_mfma_f32_16x16x32_bf16 v[44:47], v[158:161], v[182:185], v[44:47]
	v_mfma_f32_16x16x32_bf16 v[32:35], v[150:153], v[190:193], v[32:35]
	v_mfma_f32_16x16x32_bf16 v[36:39], v[158:161], v[190:193], v[36:39]
	s_setprio 0
	s_barrier
	s_add_i32 s18, s18, s4
	s_add_i32 vcc_hi, s60, 2
	s_cmp_eq_u32 vcc_hi, s83
	s_cselect_b32 s100, s16, s81
	s_cselect_b32 s101, s17, s82
	s_add_u32 s100, s100, s84
	s_addc_u32 s101, s101, 0
	s_add_u32 s100, s100, 0x80
	s_addc_u32 s101, s101, 0
	s_mov_b32 m0, s18
	s_nop 0
	global_load_lds_dwordx4 v198, s[100:101]
	s_add_i32 m0, s18, 0x2000
	s_nop 0
	global_load_lds_dwordx4 v128, s[100:101]
	s_waitcnt vmcnt(6)
	s_barrier
	s_setprio 1
	v_mfma_f32_16x16x32_bf16 v[120:123], v[194:197], v[162:165], v[120:123]
	v_mfma_f32_16x16x32_bf16 v[124:127], v[204:207], v[162:165], v[124:127]
	v_mfma_f32_16x16x32_bf16 v[112:115], v[194:197], v[170:173], v[112:115]
	v_mfma_f32_16x16x32_bf16 v[116:119], v[204:207], v[170:173], v[116:119]
	v_mfma_f32_16x16x32_bf16 v[104:107], v[194:197], v[178:181], v[104:107]
	v_mfma_f32_16x16x32_bf16 v[108:111], v[204:207], v[178:181], v[108:111]
	v_mfma_f32_16x16x32_bf16 v[92:95], v[194:197], v[186:189], v[92:95]
	v_mfma_f32_16x16x32_bf16 v[100:103], v[204:207], v[186:189], v[100:103]
	v_mfma_f32_16x16x32_bf16 v[120:123], v[200:203], v[166:169], v[120:123]
	v_mfma_f32_16x16x32_bf16 v[124:127], v[208:211], v[166:169], v[124:127]
	v_mfma_f32_16x16x32_bf16 v[112:115], v[200:203], v[174:177], v[112:115]
	v_mfma_f32_16x16x32_bf16 v[116:119], v[208:211], v[174:177], v[116:119]
	v_mfma_f32_16x16x32_bf16 v[104:107], v[200:203], v[182:185], v[104:107]
	v_mfma_f32_16x16x32_bf16 v[108:111], v[208:211], v[182:185], v[108:111]
	v_mfma_f32_16x16x32_bf16 v[92:95], v[200:203], v[190:193], v[92:95]
	v_mfma_f32_16x16x32_bf16 v[100:103], v[208:211], v[190:193], v[100:103]
	s_setprio 0
	s_add_u32 s20, s20, 0x100
	s_addc_u32 s21, s21, 0
	s_add_u32 s81, s81, 0x100
	s_addc_u32 s82, s82, 0
	s_cmp_ge_u32 s83, s57
	s_mov_b32 s18, s83
	s_barrier
	s_cbranch_scc0 .LBB0_743
	v_lshl_add_u32 v140, s80, 8, v145
	v_ashrrev_i32_e32 v138, 31, v140
	v_mul_lo_u32 v157, s78, v138
	v_mul_lo_u32 v141, s79, v140
	v_mad_u64_u32 v[138:139], s[18:19], s78, v140, 0
	v_or_b32_e32 v162, 16, v140
	v_or_b32_e32 v160, 32, v140
	v_or_b32_e32 v158, 48, v140
	v_add_u32_e32 v154, 0x80, v140
	v_add_u32_e32 v151, 0x90, v140
	v_add3_u32 v139, v139, v157, v141
	s_mov_b64 s[18:19], -1
	s_andn2_b64 vcc, exec, s[14:15]
	v_mul_lo_u32 v163, s79, v162
	v_mul_lo_u32 v161, s79, v160
	v_mul_lo_u32 v159, s79, v158
	v_ashrrev_i32_e32 v156, 31, v154
	v_mul_lo_u32 v155, s79, v154
	v_ashrrev_i32_e32 v153, 31, v151
	v_mul_lo_u32 v152, s79, v151
	v_add_u32_e32 v150, 0xa0, v140
	v_add_u32_e32 v149, 0xb0, v140
	s_cbranch_vccnz .LBB0_746
	s_lshl_b32 s100, s78, 5
	s_mov_b32 s101, 0
	v_mul_f32_e32 v140, 0xbfb8aa3b, v24
	v_mul_f32_e32 v141, 0xbfb8aa3b, v25
	v_mul_f32_e32 v166, 0xbfb8aa3b, v26
	v_mul_f32_e32 v167, 0xbfb8aa3b, v27
	v_mul_f32_e32 v168, 0xbfb8aa3b, v28
	v_mul_f32_e32 v169, 0xbfb8aa3b, v29
	v_exp_f32_e32 v140, v140
	v_exp_f32_e32 v141, v141
	v_exp_f32_e32 v166, v166
	v_exp_f32_e32 v167, v167
	v_exp_f32_e32 v168, v168
	v_exp_f32_e32 v169, v169
	v_mul_f32_e32 v170, 0xbfb8aa3b, v30
	v_mul_f32_e32 v171, 0xbfb8aa3b, v31
	v_add_f32_e32 v140, 1.0, v140
	v_add_f32_e32 v141, 1.0, v141
	v_add_f32_e32 v166, 1.0, v166
	v_add_f32_e32 v167, 1.0, v167
	v_add_f32_e32 v168, 1.0, v168
	v_add_f32_e32 v169, 1.0, v169
	v_exp_f32_e32 v170, v170
	v_exp_f32_e32 v171, v171
	v_rcp_f32_e32 v164, v140
	v_rcp_f32_e32 v165, v141
	v_rcp_f32_e32 v166, v166
	v_rcp_f32_e32 v167, v167
	v_rcp_f32_e32 v168, v168
	v_rcp_f32_e32 v169, v169
	v_add_f32_e32 v170, 1.0, v170
	v_add_f32_e32 v171, 1.0, v171
	v_pk_mul_f32 v[164:165], v[24:25], v[164:165]
	v_pk_mul_f32 v[166:167], v[26:27], v[166:167]
	v_rcp_f32_e32 v170, v170
	v_rcp_f32_e32 v171, v171
	v_pk_mul_f32 v[168:169], v[28:29], v[168:169]
	v_pk_mul_f32 v[164:165], v[164:165], v[88:89]
	v_pk_mul_f32 v[166:167], v[166:167], v[90:91]
	v_pk_mul_f32 v[168:169], v[168:169], v[96:97]
	v_cvt_pk_bf16_f32 v164, v164, v165
	v_cvt_pk_bf16_f32 v165, v166, v167
	v_cvt_pk_bf16_f32 v166, v168, v169
	v_mul_f32_e32 v168, 0xbfb8aa3b, v16
	v_mul_f32_e32 v169, 0xbfb8aa3b, v17
	v_lshl_or_b32 v140, s77, 7, v147
	v_readlane_b32 s18, v255, 30
	v_exp_f32_e32 v168, v168
	v_exp_f32_e32 v169, v169
	v_ashrrev_i32_e32 v141, 31, v140
	v_readlane_b32 s19, v255, 31
	v_pk_mul_f32 v[170:171], v[30:31], v[170:171]
	s_nop 0
	v_lshl_add_u64 v[140:141], v[140:141], 1, s[18:19]
	v_pk_mul_f32 v[170:171], v[170:171], v[98:99]
	v_lshl_add_u64 v[174:175], v[138:139], 1, v[140:141]
	v_cvt_pk_bf16_f32 v167, v170, v171
	global_store_dwordx4 v[174:175], v[164:167], off
; DI unsigned pk2(float lo, float hi) { f32x2 v = {lo, hi}; bf16v2 b = __builtin_convertvector(v, bf16v2); return __builtin_bit_cast(unsigned, b); }
; DI float silu_f(float x) { return x * __builtin_amdgcn_rcpf(1.f + __expf(-x)); }
;     DI void operator()(const f32x4 (&acc)[2][2][4][2], const Unit& u, int wr, int wc, int fr, int fq) const {
;     ...
;             for (int m = 0; m < 4; ++m) { bf16_t* rowp = O + (size_t)(row0 + ai * HALF + m * 16) * ldc + col0;
;                 float r[8];
; #pragma unroll
;                 for (int n = 0; n < 2; ++n)
; #pragma unroll
;                     for (int e = 0; e < 4; ++e) { const float g = acc[ai][0][m][n][e], up = acc[ai][1][m][n][e]; r[n * 4 + e] = silu_f(g) * up; }
;                 u32x4 o; o.x = pk2(r[0], r[1]); o.y = pk2(r[2], r[3]); o.z = pk2(r[4], r[5]); o.w = pk2(r[6], r[7]);
;                 *(u32x4*)rowp = o; }
	s_nop 1
	v_mul_f32_e32 v170, 0xbfb8aa3b, v20
	v_mul_f32_e32 v171, 0xbfb8aa3b, v21
	v_add_f32_e32 v164, 1.0, v168
	v_add_f32_e32 v165, 1.0, v169
	v_mul_f32_e32 v168, 0xbfb8aa3b, v18
	v_mul_f32_e32 v169, 0xbfb8aa3b, v19
	v_exp_f32_e32 v168, v168
	v_exp_f32_e32 v169, v169
	v_mul_f32_e32 v172, 0xbfb8aa3b, v22
	v_mul_f32_e32 v173, 0xbfb8aa3b, v23
	v_add_f32_e32 v168, 1.0, v168
	v_add_f32_e32 v169, 1.0, v169
	v_exp_f32_e32 v170, v170
	v_exp_f32_e32 v171, v171
	v_exp_f32_e32 v172, v172
	v_exp_f32_e32 v173, v173
	v_rcp_f32_e32 v164, v164
	v_rcp_f32_e32 v165, v165
	v_rcp_f32_e32 v168, v168
	v_rcp_f32_e32 v169, v169
	v_add_f32_e32 v170, 1.0, v170
	v_add_f32_e32 v171, 1.0, v171
	v_add_f32_e32 v172, 1.0, v172
	v_add_f32_e32 v173, 1.0, v173
	v_pk_mul_f32 v[164:165], v[16:17], v[164:165]
	v_pk_mul_f32 v[168:169], v[18:19], v[168:169]
	v_rcp_f32_e32 v170, v170
	v_rcp_f32_e32 v171, v171
	v_rcp_f32_e32 v172, v172
	v_rcp_f32_e32 v173, v173
	v_pk_mul_f32 v[164:165], v[164:165], v[80:81]
	v_pk_mul_f32 v[168:169], v[168:169], v[82:83]
	v_cvt_pk_bf16_f32 v164, v164, v165
	v_cvt_pk_bf16_f32 v165, v168, v169
	v_mul_f32_e32 v168, 0xbfb8aa3b, v8
	v_mul_f32_e32 v169, 0xbfb8aa3b, v9
	v_exp_f32_e32 v168, v168
	v_exp_f32_e32 v169, v169
	v_pk_mul_f32 v[170:171], v[20:21], v[170:171]
	v_pk_mul_f32 v[172:173], v[22:23], v[172:173]
	v_pk_mul_f32 v[170:171], v[170:171], v[84:85]
	v_pk_mul_f32 v[172:173], v[172:173], v[86:87]
	v_lshl_add_u64 v[174:175], v[174:175], 0, s[100:101]
	v_cvt_pk_bf16_f32 v166, v170, v171
	v_cvt_pk_bf16_f32 v167, v172, v173
	global_store_dwordx4 v[174:175], v[164:167], off
	s_nop 1
	v_mul_f32_e32 v170, 0xbfb8aa3b, v12
	v_mul_f32_e32 v171, 0xbfb8aa3b, v13
	v_add_f32_e32 v164, 1.0, v168
	v_add_f32_e32 v165, 1.0, v169
	v_mul_f32_e32 v168, 0xbfb8aa3b, v10
	v_mul_f32_e32 v169, 0xbfb8aa3b, v11
	v_exp_f32_e32 v168, v168
	v_exp_f32_e32 v169, v169
	v_mul_f32_e32 v172, 0xbfb8aa3b, v14
	v_mul_f32_e32 v173, 0xbfb8aa3b, v15
	v_add_f32_e32 v168, 1.0, v168
	v_add_f32_e32 v169, 1.0, v169
	v_exp_f32_e32 v170, v170
	v_exp_f32_e32 v171, v171
	v_exp_f32_e32 v172, v172
	v_exp_f32_e32 v173, v173
	v_rcp_f32_e32 v164, v164
	v_rcp_f32_e32 v165, v165
	v_rcp_f32_e32 v168, v168
	v_rcp_f32_e32 v169, v169
	v_add_f32_e32 v170, 1.0, v170
	v_add_f32_e32 v171, 1.0, v171
	v_add_f32_e32 v172, 1.0, v172
	v_add_f32_e32 v173, 1.0, v173
	v_pk_mul_f32 v[164:165], v[8:9], v[164:165]
	v_pk_mul_f32 v[168:169], v[10:11], v[168:169]
	v_rcp_f32_e32 v170, v170
	v_rcp_f32_e32 v171, v171
	v_rcp_f32_e32 v172, v172
	v_rcp_f32_e32 v173, v173
	v_pk_mul_f32 v[164:165], v[164:165], v[72:73]
	v_pk_mul_f32 v[168:169], v[168:169], v[74:75]
	v_cvt_pk_bf16_f32 v164, v164, v165
	v_cvt_pk_bf16_f32 v165, v168, v169
	v_mul_f32_e32 v168, 0xbfb8aa3b, v0
	v_mul_f32_e32 v169, 0xbfb8aa3b, v1
	v_exp_f32_e32 v168, v168
	v_exp_f32_e32 v169, v169
	v_pk_mul_f32 v[170:171], v[12:13], v[170:171]
	v_pk_mul_f32 v[172:173], v[14:15], v[172:173]
	v_pk_mul_f32 v[170:171], v[170:171], v[76:77]
	v_pk_mul_f32 v[172:173], v[172:173], v[78:79]
	v_lshl_add_u64 v[174:175], v[174:175], 0, s[100:101]
	v_cvt_pk_bf16_f32 v166, v170, v171
	v_cvt_pk_bf16_f32 v167, v172, v173
	global_store_dwordx4 v[174:175], v[164:167], off
	s_nop 1
	v_mul_f32_e32 v170, 0xbfb8aa3b, v4
	v_mul_f32_e32 v171, 0xbfb8aa3b, v5
	v_add_f32_e32 v164, 1.0, v168
	v_add_f32_e32 v165, 1.0, v169
	v_mul_f32_e32 v168, 0xbfb8aa3b, v2
	v_mul_f32_e32 v169, 0xbfb8aa3b, v3
	v_mul_f32_e32 v172, 0xbfb8aa3b, v6
	v_mul_f32_e32 v173, 0xbfb8aa3b, v7
	v_exp_f32_e32 v168, v168
	v_exp_f32_e32 v169, v169
	v_exp_f32_e32 v170, v170
	v_exp_f32_e32 v171, v171
	v_exp_f32_e32 v172, v172
	v_exp_f32_e32 v173, v173
	v_add_f32_e32 v168, 1.0, v168
	v_add_f32_e32 v169, 1.0, v169
	v_add_f32_e32 v170, 1.0, v170
	v_add_f32_e32 v171, 1.0, v171
	v_add_f32_e32 v172, 1.0, v172
	v_add_f32_e32 v173, 1.0, v173
	v_rcp_f32_e32 v164, v164
	v_rcp_f32_e32 v165, v165
	v_rcp_f32_e32 v168, v168
	v_rcp_f32_e32 v169, v169
	v_rcp_f32_e32 v170, v170
	v_rcp_f32_e32 v171, v171
	v_rcp_f32_e32 v172, v172
	v_rcp_f32_e32 v173, v173
	v_pk_mul_f32 v[164:165], v[0:1], v[164:165]
	v_pk_mul_f32 v[168:169], v[2:3], v[168:169]
	v_pk_mul_f32 v[170:171], v[4:5], v[170:171]
	v_pk_mul_f32 v[172:173], v[6:7], v[172:173]
	v_pk_mul_f32 v[164:165], v[164:165], v[56:57]
	v_pk_mul_f32 v[168:169], v[168:169], v[58:59]
	v_pk_mul_f32 v[170:171], v[170:171], v[64:65]
	v_pk_mul_f32 v[172:173], v[172:173], v[66:67]
	v_lshl_add_u64 v[174:175], v[174:175], 0, s[100:101]
	v_cvt_pk_bf16_f32 v164, v164, v165
	v_cvt_pk_bf16_f32 v165, v168, v169
	v_cvt_pk_bf16_f32 v166, v170, v171
	v_cvt_pk_bf16_f32 v167, v172, v173
	global_store_dwordx4 v[174:175], v[164:167], off
	s_nop 1
	v_mul_f32_e32 v169, 0xbfb8aa3b, v63
	v_mul_f32_e32 v164, 0xbfb8aa3b, v60
	v_mul_f32_e32 v165, 0xbfb8aa3b, v61
	v_mul_f32_e32 v168, 0xbfb8aa3b, v62
	v_mul_f32_e32 v170, 0xbfb8aa3b, v68
	v_mul_f32_e32 v171, 0xbfb8aa3b, v69
	v_mul_f32_e32 v172, 0xbfb8aa3b, v70
	v_mul_f32_e32 v173, 0xbfb8aa3b, v71
	v_exp_f32_e32 v164, v164
	v_exp_f32_e32 v165, v165
	v_exp_f32_e32 v168, v168
	v_exp_f32_e32 v169, v169
	v_exp_f32_e32 v170, v170
	v_exp_f32_e32 v171, v171
	v_exp_f32_e32 v172, v172
	v_exp_f32_e32 v173, v173
	v_add_f32_e32 v164, 1.0, v164
	v_add_f32_e32 v165, 1.0, v165
	v_add_f32_e32 v168, 1.0, v168
	v_add_f32_e32 v169, 1.0, v169
	v_add_f32_e32 v170, 1.0, v170
	v_add_f32_e32 v171, 1.0, v171
	v_add_f32_e32 v172, 1.0, v172
	v_add_f32_e32 v173, 1.0, v173
	v_rcp_f32_e32 v164, v164
	v_rcp_f32_e32 v165, v165
	v_rcp_f32_e32 v168, v168
	v_rcp_f32_e32 v169, v169
	v_rcp_f32_e32 v170, v170
	v_rcp_f32_e32 v171, v171
	v_rcp_f32_e32 v172, v172
; DI unsigned pk2(float lo, float hi) { f32x2 v = {lo, hi}; bf16v2 b = __builtin_convertvector(v, bf16v2); return __builtin_bit_cast(unsigned, b); }
; DI float silu_f(float x) { return x * __builtin_amdgcn_rcpf(1.f + __expf(-x)); }
;     DI void operator()(const f32x4 (&acc)[2][2][4][2], const Unit& u, int wr, int wc, int fr, int fq) const {
;     ...
;             for (int m = 0; m < 4; ++m) { bf16_t* rowp = O + (size_t)(row0 + ai * HALF + m * 16) * ldc + col0;
;                 float r[8];
; #pragma unroll
;                 for (int n = 0; n < 2; ++n)
; #pragma unroll
;                     for (int e = 0; e < 4; ++e) { const float g = acc[ai][0][m][n][e], up = acc[ai][1][m][n][e]; r[n * 4 + e] = silu_f(g) * up; }
;                 u32x4 o; o.x = pk2(r[0], r[1]); o.y = pk2(r[2], r[3]); o.z = pk2(r[4], r[5]); o.w = pk2(r[6], r[7]);
;                 *(u32x4*)rowp = o; }
	v_rcp_f32_e32 v173, v173
	v_pk_mul_f32 v[164:165], v[60:61], v[164:165]
	v_pk_mul_f32 v[168:169], v[62:63], v[168:169]
	v_pk_mul_f32 v[170:171], v[68:69], v[170:171]
	v_pk_mul_f32 v[172:173], v[70:71], v[172:173]
	v_pk_mul_f32 v[164:165], v[164:165], v[120:121]
	v_pk_mul_f32 v[168:169], v[168:169], v[122:123]
	v_pk_mul_f32 v[170:171], v[170:171], v[124:125]
	v_pk_mul_f32 v[172:173], v[172:173], v[126:127]
	s_mul_i32 vcc_lo, s78, 0xa0
	s_mov_b32 vcc_hi, 0
	v_lshl_add_u64 v[174:175], v[174:175], 0, vcc
	v_cvt_pk_bf16_f32 v164, v164, v165
	v_cvt_pk_bf16_f32 v165, v168, v169
	v_cvt_pk_bf16_f32 v166, v170, v171
	v_cvt_pk_bf16_f32 v167, v172, v173
	global_store_dwordx4 v[174:175], v[164:167], off
	s_nop 1
	v_mul_f32_e32 v169, 0xbfb8aa3b, v51
	v_mul_f32_e32 v164, 0xbfb8aa3b, v48
	v_mul_f32_e32 v165, 0xbfb8aa3b, v49
	v_mul_f32_e32 v168, 0xbfb8aa3b, v50
	v_mul_f32_e32 v170, 0xbfb8aa3b, v52
	v_mul_f32_e32 v171, 0xbfb8aa3b, v53
	v_mul_f32_e32 v172, 0xbfb8aa3b, v54
	v_mul_f32_e32 v173, 0xbfb8aa3b, v55
	v_exp_f32_e32 v164, v164
	v_exp_f32_e32 v165, v165
	v_exp_f32_e32 v168, v168
	v_exp_f32_e32 v169, v169
	v_exp_f32_e32 v170, v170
	v_exp_f32_e32 v171, v171
	v_exp_f32_e32 v172, v172
	v_exp_f32_e32 v173, v173
	v_add_f32_e32 v164, 1.0, v164
	v_add_f32_e32 v165, 1.0, v165
	v_add_f32_e32 v168, 1.0, v168
	v_add_f32_e32 v169, 1.0, v169
	v_add_f32_e32 v170, 1.0, v170
	v_add_f32_e32 v171, 1.0, v171
	v_add_f32_e32 v172, 1.0, v172
	v_add_f32_e32 v173, 1.0, v173
	v_rcp_f32_e32 v164, v164
	v_rcp_f32_e32 v165, v165
	v_rcp_f32_e32 v168, v168
	v_rcp_f32_e32 v169, v169
	v_rcp_f32_e32 v170, v170
	v_rcp_f32_e32 v171, v171
	v_rcp_f32_e32 v172, v172
	v_rcp_f32_e32 v173, v173
	v_pk_mul_f32 v[164:165], v[48:49], v[164:165]
	v_pk_mul_f32 v[168:169], v[50:51], v[168:169]
	v_pk_mul_f32 v[170:171], v[52:53], v[170:171]
	v_pk_mul_f32 v[172:173], v[54:55], v[172:173]
	v_pk_mul_f32 v[164:165], v[164:165], v[112:113]
	v_pk_mul_f32 v[168:169], v[168:169], v[114:115]
	v_pk_mul_f32 v[170:171], v[170:171], v[116:117]
	v_pk_mul_f32 v[172:173], v[172:173], v[118:119]
	v_lshl_add_u64 v[174:175], v[174:175], 0, s[100:101]
	v_cvt_pk_bf16_f32 v164, v164, v165
	v_cvt_pk_bf16_f32 v165, v168, v169
	v_cvt_pk_bf16_f32 v166, v170, v171
	v_cvt_pk_bf16_f32 v167, v172, v173
	global_store_dwordx4 v[174:175], v[164:167], off
	s_nop 1
	v_mul_f32_e32 v170, 0xbfb8aa3b, v44
	v_mul_f32_e32 v164, 0xbfb8aa3b, v40
	v_mul_f32_e32 v165, 0xbfb8aa3b, v41
	v_mul_f32_e32 v168, 0xbfb8aa3b, v42
	v_mul_f32_e32 v169, 0xbfb8aa3b, v43
	v_mul_f32_e32 v171, 0xbfb8aa3b, v45
	v_mul_f32_e32 v172, 0xbfb8aa3b, v46
	v_mul_f32_e32 v173, 0xbfb8aa3b, v47
	v_exp_f32_e32 v164, v164
	v_exp_f32_e32 v165, v165
	v_exp_f32_e32 v168, v168
	v_exp_f32_e32 v169, v169
	v_exp_f32_e32 v170, v170
	v_exp_f32_e32 v171, v171
	v_exp_f32_e32 v172, v172
	v_exp_f32_e32 v173, v173
	v_add_f32_e32 v164, 1.0, v164
	v_add_f32_e32 v165, 1.0, v165
	v_add_f32_e32 v168, 1.0, v168
	v_add_f32_e32 v169, 1.0, v169
	v_add_f32_e32 v170, 1.0, v170
	v_add_f32_e32 v171, 1.0, v171
	v_add_f32_e32 v172, 1.0, v172
	v_add_f32_e32 v173, 1.0, v173
	v_rcp_f32_e32 v164, v164
	v_rcp_f32_e32 v165, v165
	v_rcp_f32_e32 v168, v168
	v_rcp_f32_e32 v169, v169
	v_rcp_f32_e32 v170, v170
	v_rcp_f32_e32 v171, v171
	v_rcp_f32_e32 v172, v172
	v_rcp_f32_e32 v173, v173
	v_pk_mul_f32 v[164:165], v[40:41], v[164:165]
	v_pk_mul_f32 v[168:169], v[42:43], v[168:169]
	v_pk_mul_f32 v[170:171], v[44:45], v[170:171]
	v_pk_mul_f32 v[172:173], v[46:47], v[172:173]
	v_pk_mul_f32 v[164:165], v[164:165], v[104:105]
	v_pk_mul_f32 v[168:169], v[168:169], v[106:107]
	v_pk_mul_f32 v[170:171], v[170:171], v[108:109]
	v_pk_mul_f32 v[172:173], v[172:173], v[110:111]
	v_lshl_add_u64 v[174:175], v[174:175], 0, s[100:101]
	v_cvt_pk_bf16_f32 v164, v164, v165
	v_cvt_pk_bf16_f32 v165, v168, v169
	v_cvt_pk_bf16_f32 v166, v170, v171
	v_cvt_pk_bf16_f32 v167, v172, v173
	global_store_dwordx4 v[174:175], v[164:167], off
	s_nop 1
	v_mul_f32_e32 v170, 0xbfb8aa3b, v36
	v_mul_f32_e32 v164, 0xbfb8aa3b, v32
	v_mul_f32_e32 v165, 0xbfb8aa3b, v33
	v_mul_f32_e32 v168, 0xbfb8aa3b, v34
	v_mul_f32_e32 v169, 0xbfb8aa3b, v35
	v_mul_f32_e32 v171, 0xbfb8aa3b, v37
	v_mul_f32_e32 v172, 0xbfb8aa3b, v38
	v_mul_f32_e32 v173, 0xbfb8aa3b, v39
	v_exp_f32_e32 v164, v164
	v_exp_f32_e32 v165, v165
	v_exp_f32_e32 v168, v168
	v_exp_f32_e32 v169, v169
	v_exp_f32_e32 v170, v170
	v_exp_f32_e32 v171, v171
	v_exp_f32_e32 v172, v172
	v_exp_f32_e32 v173, v173
	v_add_f32_e32 v164, 1.0, v164
	v_add_f32_e32 v165, 1.0, v165
	v_add_f32_e32 v168, 1.0, v168
	v_add_f32_e32 v169, 1.0, v169
	v_add_f32_e32 v170, 1.0, v170
	v_add_f32_e32 v171, 1.0, v171
	v_add_f32_e32 v172, 1.0, v172
	v_add_f32_e32 v173, 1.0, v173
	v_rcp_f32_e32 v164, v164
	v_rcp_f32_e32 v165, v165
	v_rcp_f32_e32 v168, v168
	v_rcp_f32_e32 v169, v169
	v_rcp_f32_e32 v170, v170
	v_rcp_f32_e32 v171, v171
	v_rcp_f32_e32 v172, v172
	v_rcp_f32_e32 v173, v173
	v_pk_mul_f32 v[164:165], v[32:33], v[164:165]
	v_pk_mul_f32 v[168:169], v[34:35], v[168:169]
	v_pk_mul_f32 v[170:171], v[36:37], v[170:171]
	v_pk_mul_f32 v[172:173], v[38:39], v[172:173]
	v_pk_mul_f32 v[164:165], v[164:165], v[92:93]
	v_pk_mul_f32 v[168:169], v[168:169], v[94:95]
	v_pk_mul_f32 v[170:171], v[170:171], v[100:101]
	v_pk_mul_f32 v[172:173], v[172:173], v[102:103]
	v_lshl_add_u64 v[174:175], v[174:175], 0, s[100:101]
	v_cvt_pk_bf16_f32 v164, v164, v165
	v_cvt_pk_bf16_f32 v165, v168, v169
	v_cvt_pk_bf16_f32 v166, v170, v171
	v_cvt_pk_bf16_f32 v167, v172, v173
	global_store_dwordx4 v[174:175], v[164:167], off
	s_nop 1
	s_cbranch_execnz .LBB0_748
	s_branch .LBB0_747

; DI unsigned pk2(float lo, float hi) { f32x2 v = {lo, hi}; bf16v2 b = __builtin_convertvector(v, bf16v2); return __builtin_bit_cast(unsigned, b); }
;     DI void operator()(const f32x4 (&acc)[2][2][4][2], const Unit& u, int wr, int wc, int fr, int fq) const {
;         const int row0 = u.pm * BM + wr * 64 + fr, col0 = u.pn * BM + wc * 32 + 8 * fq;
; #pragma unroll
;         for (int ai = 0; ai < 2; ++ai)
; #pragma unroll
;             for (int m = 0; m < 4; ++m) { bf16_t* rowp = O + (size_t)(row0 + ai * HALF + m * 16) * ldc + col0;
; #pragma unroll
;                 for (int bj = 0; bj < 2; ++bj) { const f32x4 v0 = acc[ai][bj][m][0], v1 = acc[ai][bj][m][1];
;                     u32x4 o; o.x = pk2(v0[0], v0[1]); o.y = pk2(v0[2], v0[3]); o.z = pk2(v1[0], v1[1]); o.w = pk2(v1[2], v1[3]);
;                     *(u32x4*)(rowp + bj * HALF) = o; } }
;     }
.LBB0_747:
	s_lshl_b32 s100, s78, 5
	s_mov_b32 s101, 0
	v_lshl_or_b32 v140, s77, 8, v147
	v_readlane_b32 s18, v255, 30
	v_ashrrev_i32_e32 v141, 31, v140
	v_readlane_b32 s19, v255, 31
	v_cvt_pk_bf16_f32 v24, v24, v25
	v_cvt_pk_bf16_f32 v25, v26, v27
	v_lshl_add_u64 v[140:141], v[140:141], 1, s[18:19]
	v_lshl_add_u64 v[138:139], v[138:139], 1, v[140:141]
	v_cvt_pk_bf16_f32 v26, v28, v29
	v_cvt_pk_bf16_f32 v27, v30, v31
	global_store_dwordx4 v[138:139], v[24:27], off
	v_cvt_pk_bf16_f32 v16, v16, v17
	v_cvt_pk_bf16_f32 v17, v18, v19
	v_cvt_pk_bf16_f32 v24, v88, v89
	v_cvt_pk_bf16_f32 v25, v90, v91
	v_cvt_pk_bf16_f32 v26, v96, v97
	v_cvt_pk_bf16_f32 v27, v98, v99
	global_store_dwordx4 v[138:139], v[24:27], off offset:256
	v_cvt_pk_bf16_f32 v18, v20, v21
	v_cvt_pk_bf16_f32 v19, v22, v23
	v_lshl_add_u64 v[24:25], v[138:139], 0, s[100:101]
	global_store_dwordx4 v[24:25], v[16:19], off
	v_cvt_pk_bf16_f32 v8, v8, v9
	v_cvt_pk_bf16_f32 v9, v10, v11
	v_cvt_pk_bf16_f32 v16, v80, v81
	v_cvt_pk_bf16_f32 v17, v82, v83
	v_cvt_pk_bf16_f32 v18, v84, v85
	v_cvt_pk_bf16_f32 v19, v86, v87
	global_store_dwordx4 v[24:25], v[16:19], off offset:256
	v_cvt_pk_bf16_f32 v10, v12, v13
	v_cvt_pk_bf16_f32 v11, v14, v15
	v_lshl_add_u64 v[16:17], v[24:25], 0, s[100:101]
	global_store_dwordx4 v[16:17], v[8:11], off
	v_cvt_pk_bf16_f32 v0, v0, v1
	v_cvt_pk_bf16_f32 v1, v2, v3
	v_cvt_pk_bf16_f32 v8, v72, v73
	v_cvt_pk_bf16_f32 v9, v74, v75
	v_cvt_pk_bf16_f32 v10, v76, v77
	v_cvt_pk_bf16_f32 v11, v78, v79
	global_store_dwordx4 v[16:17], v[8:11], off offset:256
	v_cvt_pk_bf16_f32 v2, v4, v5
	v_cvt_pk_bf16_f32 v3, v6, v7
	v_lshl_add_u64 v[8:9], v[16:17], 0, s[100:101]
	global_store_dwordx4 v[8:9], v[0:3], off
	s_nop 1
	v_cvt_pk_bf16_f32 v0, v56, v57
	v_cvt_pk_bf16_f32 v1, v58, v59
	v_cvt_pk_bf16_f32 v2, v64, v65
	v_cvt_pk_bf16_f32 v3, v66, v67
	global_store_dwordx4 v[8:9], v[0:3], off offset:256
	s_nop 1
	s_mul_i32 vcc_lo, s78, 0xa0
	s_mov_b32 vcc_hi, 0
	v_lshl_add_u64 v[4:5], v[8:9], 0, vcc
	v_cvt_pk_bf16_f32 v0, v60, v61
	v_cvt_pk_bf16_f32 v1, v62, v63
	v_cvt_pk_bf16_f32 v2, v68, v69
	v_cvt_pk_bf16_f32 v3, v70, v71
	global_store_dwordx4 v[4:5], v[0:3], off
	s_nop 1
	v_cvt_pk_bf16_f32 v0, v120, v121
	v_cvt_pk_bf16_f32 v1, v122, v123
	v_cvt_pk_bf16_f32 v2, v124, v125
	v_cvt_pk_bf16_f32 v3, v126, v127
	global_store_dwordx4 v[4:5], v[0:3], off offset:256
	s_nop 1
	v_lshl_add_u64 v[4:5], v[4:5], 0, s[100:101]
	v_cvt_pk_bf16_f32 v0, v48, v49
	v_cvt_pk_bf16_f32 v1, v50, v51
	v_cvt_pk_bf16_f32 v2, v52, v53
	v_cvt_pk_bf16_f32 v3, v54, v55
	global_store_dwordx4 v[4:5], v[0:3], off
	s_nop 1
	v_cvt_pk_bf16_f32 v0, v112, v113
	v_cvt_pk_bf16_f32 v1, v114, v115
	v_cvt_pk_bf16_f32 v2, v116, v117
	v_cvt_pk_bf16_f32 v3, v118, v119
	global_store_dwordx4 v[4:5], v[0:3], off offset:256
	s_nop 1
	v_lshl_add_u64 v[4:5], v[4:5], 0, s[100:101]
	v_cvt_pk_bf16_f32 v0, v40, v41
	v_cvt_pk_bf16_f32 v1, v42, v43
	v_cvt_pk_bf16_f32 v2, v44, v45
	v_cvt_pk_bf16_f32 v3, v46, v47
	global_store_dwordx4 v[4:5], v[0:3], off
	s_nop 1
	v_cvt_pk_bf16_f32 v0, v104, v105
	v_cvt_pk_bf16_f32 v1, v106, v107
	v_cvt_pk_bf16_f32 v2, v108, v109
	v_cvt_pk_bf16_f32 v3, v110, v111
	global_store_dwordx4 v[4:5], v[0:3], off offset:256
	s_nop 1
	v_lshl_add_u64 v[4:5], v[4:5], 0, s[100:101]
	v_cvt_pk_bf16_f32 v0, v32, v33
	v_cvt_pk_bf16_f32 v1, v34, v35
	v_cvt_pk_bf16_f32 v2, v36, v37
	v_cvt_pk_bf16_f32 v3, v38, v39
	global_store_dwordx4 v[4:5], v[0:3], off
	s_nop 1
	v_cvt_pk_bf16_f32 v0, v92, v93
	v_cvt_pk_bf16_f32 v1, v94, v95
	v_cvt_pk_bf16_f32 v2, v100, v101
	v_cvt_pk_bf16_f32 v3, v102, v103
	global_store_dwordx4 v[4:5], v[0:3], off offset:256
